# v52 plus unit-header index arithmetic: division by gsz (always 8 for these row-tile counts) as shift and mask instead of the generic v_rcp-based signed division
# speedup vs baseline: 1.0039x; 1.0039x over previous
;     __device__ bool next(int i, Unit& u) const {
;         const long L = (long)i * G + c; if (L >= nwg) return false;
;         int wgid = (int)L; { const int q = nwg / NXCD, r = nwg % NXCD, xcd = wgid % NXCD, off = wgid / NXCD; wgid = (xcd < r ? xcd * (q + 1) : r * (q + 1) + (xcd - r) * q) + off; }
;         const int nig = WGM * nN, gid = wgid / nig, fm = gid * WGM, gsz = (nM - fm) < WGM ? (nM - fm) : WGM;
;         u.pm = fm + ((wgid % nig) % gsz); u.pn = (wgid % nig) / gsz; return true;
;     }
.LBB0_195:
	s_add_i32 s70, s70, 1
	s_mul_i32 s2, s70, s62
	s_mul_hi_u32 s3, s70, s53
	s_add_i32 s3, s3, s2
	s_mul_i32 s2, s70, s53
	v_readlane_b32 s4, v255, 29
	s_add_u32 s2, s2, s4
	s_addc_u32 s3, s3, s63
	v_mov_b64_e32 v[2:3], 0x900
	v_cmp_lt_i64_e64 s[4:5], s[2:3], v[2:3]
	v_mov_b64_e32 v[2:3], 0x8ff
	v_cmp_gt_i64_e32 vcc, s[2:3], v[2:3]
	s_nop 3
	s_mov_b32 s101, s4
	s_cbranch_vccnz .LBB0_197
	s_ashr_i32 s3, s2, 31
	s_lshr_b32 s3, s3, 29
	s_add_i32 s3, s2, s3
	s_ashr_i32 s9, s3, 3
	s_and_b32 s3, s3, -8
	s_sub_i32 s2, s2, s3
	s_cmp_lt_i32 s2, 0
	s_cselect_b32 s3, s95, 0x120
	s_mul_i32 s2, s2, s3
	s_add_i32 s2, s2, s9
	s_ashr_i32 s3, s2, 31
	s_lshr_b32 s3, s3, 24
	s_add_i32 s3, s2, s3
	s_ashr_i32 s9, s3, 8
	s_lshl_b32 s9, s9, 3
	s_sub_i32 s20, 0x48, s9
	s_min_i32 s21, s20, 8
	s_and_b32 s3, s3, 0xffffff00
	s_sub_i32 s2, s2, s3
	s_ashr_i32 s20, s2, 3
	s_and_b32 s2, s2, 7
	s_add_i32 s22, s9, s2

;     __device__ bool next(int i, Unit& u) const {
;         const long L = (long)i * G + c; if (L >= nwg) return false;
;         int wgid = (int)L; { const int q = nwg / NXCD, r = nwg % NXCD, xcd = wgid % NXCD, off = wgid / NXCD; wgid = (xcd < r ? xcd * (q + 1) : r * (q + 1) + (xcd - r) * q) + off; }
;         const int nig = WGM * nN, gid = wgid / nig, fm = gid * WGM, gsz = (nM - fm) < WGM ? (nM - fm) : WGM;
;         u.pm = fm + ((wgid % nig) % gsz); u.pn = (wgid % nig) / gsz; return true;
;     }
.LBB0_698:
	s_add_i32 s23, s23, 1
	s_mul_i32 s2, s23, s75
	s_mul_hi_u32 s3, s23, s53
	s_add_i32 s3, s3, s2
	s_mul_i32 s2, s23, s53
	v_readlane_b32 s4, v255, 29
	s_add_u32 s2, s2, s4
	s_addc_u32 s3, s3, s78
	v_mov_b64_e32 v[2:3], 0x288
	v_cmp_lt_i64_e64 s[4:5], s[2:3], v[2:3]
	v_mov_b64_e32 v[2:3], 0x287
	v_cmp_gt_i64_e32 vcc, s[2:3], v[2:3]
	s_nop 3
	s_mov_b32 s101, s4
	s_cbranch_vccnz .LBB0_700
	s_ashr_i32 s3, s2, 31
	s_lshr_b32 s3, s3, 29
	s_add_i32 s3, s2, s3
	s_ashr_i32 s9, s3, 3
	s_and_b32 s3, s3, -8
	s_sub_i32 s2, s2, s3
	s_cmp_lt_i32 s2, 0
	s_movk_i32 s3, 0x52
	s_cselect_b32 s3, s3, 0x51
	s_mul_i32 s2, s2, s3
	s_add_i32 s2, s2, s9
	s_mul_hi_i32 s3, s2, 0x38e38e39
	s_lshr_b32 s9, s3, 31
	s_ashr_i32 s3, s3, 4
	s_add_i32 s3, s3, s9
	s_lshl_b32 s9, s3, 3
	s_sub_i32 s26, 0x48, s9
	s_min_i32 s27, s26, 8
	s_mulk_i32 s3, 0x48
	s_sub_i32 s2, s2, s3
	s_ashr_i32 s26, s2, 3
	s_and_b32 s2, s2, 7
	s_add_i32 s28, s9, s2

;     __device__ __forceinline__ size_t aoff(const Unit& u) const { return (size_t)u.pm * bm * lda * 2; }
;     __device__ __forceinline__ size_t boff(const Unit& u) const { return (size_t)u.pn * BM * ldb * 2; }
;     __device__ __forceinline__ size_t aoff(const Unit& u) const { return ((size_t)u.pm * BM * lda + (size_t)u.pn * akoff) * 2; }
;     __device__ __forceinline__ size_t boff(const Unit& u) const { return (size_t)u.pn * BM * ldb * 2; }
;     __device__ __forceinline__ size_t aoff(const Unit& u) const { return ((size_t)u.pm * BM * lda + (size_t)(u.pn >> 1) * akoff) * 2; }
;     __device__ __forceinline__ size_t boff(const Unit& u) const { return (size_t)u.pn * BM * ldb * 2; }
; #define PG8_STAGE(bufoff, gbase, voff) do { _Pragma("unroll") for (int _i = 0; _i < 2; ++_i) \
;         __builtin_amdgcn_global_load_lds((const unsigned*)((const char*)(gbase) + (voff)[_i]), (LAS unsigned*)(lds + (bufoff) + ldsw + _i * 8192), 16, 0, 0); } while (0)
; #define PG8_SCHED __builtin_amdgcn_sched_barrier(0)
;     __device__ bool next(int i, Unit& u) const {
;         const long L = (long)i * G + c; if (L >= nwg) return false;
;         int wgid = (int)L; { const int q = nwg / NXCD, r = nwg % NXCD, xcd = wgid % NXCD, off = wgid / NXCD; wgid = (xcd < r ? xcd * (q + 1) : r * (q + 1) + (xcd - r) * q) + off; }
;         const int nig = WGM * nN, gid = wgid / nig, fm = gid * WGM, gsz = (nM - fm) < WGM ? (nM - fm) : WGM;
;         u.pm = fm + ((wgid % nig) % gsz); u.pn = (wgid % nig) / gsz; return true;
;     }
;     ...
;         const bool has_next = S.next(ui + 1, nxt);
;         const char* nA = has_next ? (const char*)g.A + S.aoff(nxt) : cA; const char* nB = has_next ? (const char*)g.Bt + S.boff(nxt) : cB;
;         if constexpr (Epi::PRE) E.pre(lds, cur, wid);
;         for (int t = 0; t < nt; t += 2) {
;             const bool last = (t == nt - 2);
;             const char* a1 = cA + (size_t)(t + 1) * kstep;
;             const char* a2 = last ? nA : cA + (size_t)(t + 2) * kstep; const char* b2 = last ? nB : cB + (size_t)(t + 2) * kstep;
;             const char* a3 = a2 + kstep; const char* b3 = b2 + kstep;
;             if constexpr (SP2) {
;             PG8_LDB(B0, 0, 0); PG8_LDB(B1, 0, 1); PG8_SCHED; PG8_LDA(At, 0, 0); PG8_STAGE(PG8_SA(1, 1), a1 + hstepA, voffA);
.LBB0_1189:
	s_add_i32 s47, s47, 1
	s_mul_i32 s2, s47, s92
	s_mul_hi_u32 s3, s47, s53
	s_add_i32 s3, s3, s2
	s_mul_i32 s2, s47, s53
	v_readlane_b32 s4, v255, 29
	s_add_u32 s2, s2, s4
	s_addc_u32 s3, s3, s93
	v_mov_b64_e32 v[2:3], 0x1b0
	v_cmp_lt_i64_e64 s[4:5], s[2:3], v[2:3]
	v_mov_b64_e32 v[2:3], 0x1af
	v_cmp_gt_i64_e32 vcc, s[2:3], v[2:3]
	s_nop 3
	s_mov_b32 s101, s4
	s_cbranch_vccnz .LBB0_1191
	s_ashr_i32 s3, s2, 31
	s_lshr_b32 s3, s3, 29
	s_add_i32 s3, s2, s3
	s_ashr_i32 s7, s3, 3
	s_and_b32 s3, s3, -8
	s_sub_i32 s2, s2, s3
	s_cmp_lt_i32 s2, 0
	s_cselect_b32 s3, 55, 54
	s_mul_i32 s2, s2, s3
	s_add_i32 s2, s2, s7
	s_mul_hi_i32 s3, s2, 0x2aaaaaab
	s_lshr_b32 s7, s3, 31
	s_ashr_i32 s3, s3, 3
	s_add_i32 s3, s3, s7
	s_lshl_b32 s7, s3, 3
	s_sub_i32 s9, 0x48, s7
	s_min_i32 s9, s9, 8
	s_mul_i32 s3, s3, 48
	s_sub_i32 s2, s2, s3
	s_ashr_i32 s24, s2, 3
	s_and_b32 s2, s2, 7
	s_add_i32 s26, s7, s2

;     __device__ bool next(int i, Unit& u) const {
;         const long L = (long)i * G + c; if (L >= nwg) return false;
;         int wgid = (int)L; { const int q = nwg / NXCD, r = nwg % NXCD, xcd = wgid % NXCD, off = wgid / NXCD; wgid = (xcd < r ? xcd * (q + 1) : r * (q + 1) + (xcd - r) * q) + off; }
;         const int nig = WGM * nN, gid = wgid / nig, fm = gid * WGM, gsz = (nM - fm) < WGM ? (nM - fm) : WGM;
;         u.pm = fm + ((wgid % nig) % gsz); u.pn = (wgid % nig) / gsz; return true;
;     }
.LBB0_1450:
	s_ashr_i32 s2, s4, 3
	s_add_i32 s2, s14, s2
	s_ashr_i32 s3, s2, 31
	s_lshr_b32 s3, s3, 26
	s_add_i32 s3, s2, s3
	s_ashr_i32 s4, s3, 6
	s_lshl_b32 s4, s4, 3
	s_sub_i32 s5, 64, s4
	s_min_i32 s5, s5, 8
	s_andn2_b32 s3, s3, 63
	s_sub_i32 s2, s2, s3
	s_ashr_i32 s14, s2, 3
	s_and_b32 s2, s2, 7
	s_add_i32 s70, s4, s2

;     __device__ __forceinline__ size_t aoff(const Unit& u) const { return (size_t)u.pm * bm * lda * 2; }
;     __device__ __forceinline__ size_t boff(const Unit& u) const { return (size_t)u.pn * BM * ldb * 2; }
;     __device__ __forceinline__ size_t aoff(const Unit& u) const { return ((size_t)u.pm * BM * lda + (size_t)u.pn * akoff) * 2; }
;     __device__ __forceinline__ size_t boff(const Unit& u) const { return (size_t)u.pn * BM * ldb * 2; }
;     __device__ __forceinline__ size_t aoff(const Unit& u) const { return ((size_t)u.pm * BM * lda + (size_t)(u.pn >> 1) * akoff) * 2; }
;     __device__ __forceinline__ size_t boff(const Unit& u) const { return (size_t)u.pn * BM * ldb * 2; }
; #define PG8_STAGE(bufoff, gbase, voff) do { _Pragma("unroll") for (int _i = 0; _i < 2; ++_i) \
;         __builtin_amdgcn_global_load_lds((const unsigned*)((const char*)(gbase) + (voff)[_i]), (LAS unsigned*)(lds + (bufoff) + ldsw + _i * 8192), 16, 0, 0); } while (0)
; #define PG8_SCHED __builtin_amdgcn_sched_barrier(0)
;     __device__ bool next(int i, Unit& u) const {
;         const long L = (long)i * G + c; if (L >= nwg) return false;
;         int wgid = (int)L; { const int q = nwg / NXCD, r = nwg % NXCD, xcd = wgid % NXCD, off = wgid / NXCD; wgid = (xcd < r ? xcd * (q + 1) : r * (q + 1) + (xcd - r) * q) + off; }
;         const int nig = WGM * nN, gid = wgid / nig, fm = gid * WGM, gsz = (nM - fm) < WGM ? (nM - fm) : WGM;
;         u.pm = fm + ((wgid % nig) % gsz); u.pn = (wgid % nig) / gsz; return true;
;     }
;     ...
;         const bool has_next = S.next(ui + 1, nxt);
;         const char* nA = has_next ? (const char*)g.A + S.aoff(nxt) : cA; const char* nB = has_next ? (const char*)g.Bt + S.boff(nxt) : cB;
;         if constexpr (Epi::PRE) E.pre(lds, cur, wid);
;         for (int t = 0; t < nt; t += 2) {
;             const bool last = (t == nt - 2);
;             const char* a1 = cA + (size_t)(t + 1) * kstep;
;             const char* a2 = last ? nA : cA + (size_t)(t + 2) * kstep; const char* b2 = last ? nB : cB + (size_t)(t + 2) * kstep;
;             const char* a3 = a2 + kstep; const char* b3 = b2 + kstep;
;             if constexpr (SP2) {
;             PG8_LDB(B0, 0, 0); PG8_LDB(B1, 0, 1); PG8_SCHED; PG8_LDA(At, 0, 0); PG8_STAGE(PG8_SA(1, 1), a1 + hstepA, voffA);
.LBB0_1645:
	s_add_i32 s54, s54, 1
	s_mul_i32 s2, s54, s48
	s_mul_hi_u32 s3, s54, s53
	s_add_i32 s3, s3, s2
	s_mul_i32 s2, s54, s53
	v_readlane_b32 s6, v255, 29
	s_add_u32 s2, s2, s6
	s_addc_u32 s3, s3, s49
	v_mov_b64_e32 v[2:3], 0x300
	v_cmp_lt_i64_e64 s[8:9], s[2:3], v[2:3]
	v_mov_b64_e32 v[2:3], 0x2ff
	v_cmp_gt_i64_e32 vcc, s[2:3], v[2:3]
	s_nop 3
	s_mov_b32 s101, s8
	s_cbranch_vccnz .LBB0_1647
	s_ashr_i32 s3, s2, 31
	s_lshr_b32 s3, s3, 29
	s_add_i32 s3, s2, s3
	s_ashr_i32 s6, s3, 3
	s_and_b32 s3, s3, -8
	s_sub_i32 s2, s2, s3
	s_cmp_lt_i32 s2, 0
	s_movk_i32 s3, 0x61
	s_cselect_b32 s3, s3, 0x60
	s_mul_i32 s2, s2, s3
	s_add_i32 s2, s2, s6
	s_ashr_i32 s3, s2, 31
	s_lshr_b32 s3, s3, 26
	s_add_i32 s3, s2, s3
	s_ashr_i32 s6, s3, 6
	s_lshl_b32 s6, s6, 3
	s_sub_i32 s7, 0x60, s6
	s_min_i32 s7, s7, 8
	s_andn2_b32 s3, s3, 63
	s_sub_i32 s2, s2, s3
	s_ashr_i32 s14, s2, 3
	s_and_b32 s2, s2, 7
	s_add_i32 s56, s6, s2

;     __device__ __forceinline__ size_t aoff(const Unit& u) const { return (size_t)u.pm * bm * lda * 2; }
;     __device__ __forceinline__ size_t boff(const Unit& u) const { return (size_t)u.pn * BM * ldb * 2; }
;     __device__ __forceinline__ size_t aoff(const Unit& u) const { return ((size_t)u.pm * BM * lda + (size_t)u.pn * akoff) * 2; }
;     __device__ __forceinline__ size_t boff(const Unit& u) const { return (size_t)u.pn * BM * ldb * 2; }
;     __device__ __forceinline__ size_t aoff(const Unit& u) const { return ((size_t)u.pm * BM * lda + (size_t)(u.pn >> 1) * akoff) * 2; }
;     __device__ __forceinline__ size_t boff(const Unit& u) const { return (size_t)u.pn * BM * ldb * 2; }
; #define PG8_STAGE(bufoff, gbase, voff) do { _Pragma("unroll") for (int _i = 0; _i < 2; ++_i) \
;         __builtin_amdgcn_global_load_lds((const unsigned*)((const char*)(gbase) + (voff)[_i]), (LAS unsigned*)(lds + (bufoff) + ldsw + _i * 8192), 16, 0, 0); } while (0)
; #define PG8_SCHED __builtin_amdgcn_sched_barrier(0)
;     __device__ bool next(int i, Unit& u) const {
;         const long L = (long)i * G + c; if (L >= nwg) return false;
;         int wgid = (int)L; { const int q = nwg / NXCD, r = nwg % NXCD, xcd = wgid % NXCD, off = wgid / NXCD; wgid = (xcd < r ? xcd * (q + 1) : r * (q + 1) + (xcd - r) * q) + off; }
;         const int nig = WGM * nN, gid = wgid / nig, fm = gid * WGM, gsz = (nM - fm) < WGM ? (nM - fm) : WGM;
;         u.pm = fm + ((wgid % nig) % gsz); u.pn = (wgid % nig) / gsz; return true;
;     }
;     ...
;         const bool has_next = S.next(ui + 1, nxt);
;         const char* nA = has_next ? (const char*)g.A + S.aoff(nxt) : cA; const char* nB = has_next ? (const char*)g.Bt + S.boff(nxt) : cB;
;         if constexpr (Epi::PRE) E.pre(lds, cur, wid);
;         for (int t = 0; t < nt; t += 2) {
;             const bool last = (t == nt - 2);
;             const char* a1 = cA + (size_t)(t + 1) * kstep;
;             const char* a2 = last ? nA : cA + (size_t)(t + 2) * kstep; const char* b2 = last ? nB : cB + (size_t)(t + 2) * kstep;
;             const char* a3 = a2 + kstep; const char* b3 = b2 + kstep;
;             if constexpr (SP2) {
;             PG8_LDB(B0, 0, 0); PG8_LDB(B1, 0, 1); PG8_SCHED; PG8_LDA(At, 0, 0); PG8_STAGE(PG8_SA(1, 1), a1 + hstepA, voffA);
.LBB0_1770:
	s_add_i32 s78, s78, 1
	s_mul_i32 s2, s78, s89
	s_mul_hi_u32 s3, s78, s53
	s_add_i32 s3, s3, s2
	s_mul_i32 s2, s78, s53
	s_add_u32 s2, s2, s46
	s_addc_u32 s3, s3, s52
	v_mov_b64_e32 v[2:3], 0xc60
	v_cmp_lt_i64_e64 s[6:7], s[2:3], v[2:3]
	v_mov_b64_e32 v[2:3], 0xc5f
	v_cmp_gt_i64_e32 vcc, s[2:3], v[2:3]
	s_nop 3
	s_mov_b32 s101, s6
	s_cbranch_vccnz .LBB0_1772
	s_ashr_i32 s3, s2, 31
	s_lshr_b32 s3, s3, 29
	s_add_i32 s3, s2, s3
	s_ashr_i32 s9, s3, 3
	s_and_b32 s3, s3, -8
	s_sub_i32 s2, s2, s3
	s_cmp_lt_i32 s2, 0
	s_movk_i32 s3, 0x18d
	s_cselect_b32 s3, s3, 0x18c
	s_mul_i32 s2, s2, s3
	s_add_i32 s2, s2, s9
	s_mul_hi_i32 s3, s2, 0x2e8ba2e9
	s_lshr_b32 s9, s3, 31
	s_ashr_i32 s3, s3, 6
	s_add_i32 s3, s3, s9
	s_lshl_b32 s9, s3, 3
	s_sub_i32 s11, 0x48, s9
	s_min_i32 s11, s11, 8
	s_mulk_i32 s3, 0x160
	s_sub_i32 s2, s2, s3
	s_ashr_i32 s36, s2, 3
	s_and_b32 s2, s2, 7
	s_add_i32 s40, s9, s2

;     __device__ __forceinline__ size_t aoff(const Unit& u) const { return (size_t)u.pm * bm * lda * 2; }
;     __device__ __forceinline__ size_t boff(const Unit& u) const { return (size_t)u.pn * BM * ldb * 2; }
;     __device__ __forceinline__ size_t aoff(const Unit& u) const { return ((size_t)u.pm * BM * lda + (size_t)u.pn * akoff) * 2; }
;     __device__ __forceinline__ size_t boff(const Unit& u) const { return (size_t)u.pn * BM * ldb * 2; }
;     __device__ __forceinline__ size_t aoff(const Unit& u) const { return ((size_t)u.pm * BM * lda + (size_t)(u.pn >> 1) * akoff) * 2; }
;     __device__ __forceinline__ size_t boff(const Unit& u) const { return (size_t)u.pn * BM * ldb * 2; }
; #define PG8_STAGE(bufoff, gbase, voff) do { _Pragma("unroll") for (int _i = 0; _i < 2; ++_i) \
;         __builtin_amdgcn_global_load_lds((const unsigned*)((const char*)(gbase) + (voff)[_i]), (LAS unsigned*)(lds + (bufoff) + ldsw + _i * 8192), 16, 0, 0); } while (0)
; #define PG8_SCHED __builtin_amdgcn_sched_barrier(0)
;     __device__ bool next(int i, Unit& u) const {
;         const long L = (long)i * G + c; if (L >= nwg) return false;
;         int wgid = (int)L; { const int q = nwg / NXCD, r = nwg % NXCD, xcd = wgid % NXCD, off = wgid / NXCD; wgid = (xcd < r ? xcd * (q + 1) : r * (q + 1) + (xcd - r) * q) + off; }
;         const int nig = WGM * nN, gid = wgid / nig, fm = gid * WGM, gsz = (nM - fm) < WGM ? (nM - fm) : WGM;
;         u.pm = fm + ((wgid % nig) % gsz); u.pn = (wgid % nig) / gsz; return true;
;     }
;     ...
;         const bool has_next = S.next(ui + 1, nxt);
;         const char* nA = has_next ? (const char*)g.A + S.aoff(nxt) : cA; const char* nB = has_next ? (const char*)g.Bt + S.boff(nxt) : cB;
;         if constexpr (Epi::PRE) E.pre(lds, cur, wid);
;         for (int t = 0; t < nt; t += 2) {
;             const bool last = (t == nt - 2);
;             const char* a1 = cA + (size_t)(t + 1) * kstep;
;             const char* a2 = last ? nA : cA + (size_t)(t + 2) * kstep; const char* b2 = last ? nB : cB + (size_t)(t + 2) * kstep;
;             const char* a3 = a2 + kstep; const char* b3 = b2 + kstep;
;             if constexpr (SP2) {
;             PG8_LDB(B0, 0, 0); PG8_LDB(B1, 0, 1); PG8_SCHED; PG8_LDA(At, 0, 0); PG8_STAGE(PG8_SA(1, 1), a1 + hstepA, voffA);
.LBB0_2151:
	s_add_i32 s54, s54, 1
	s_mul_i32 s2, s54, s48
	s_mul_hi_u32 s3, s54, s53
	s_add_i32 s3, s3, s2
	s_mul_i32 s2, s54, s53
	v_readlane_b32 s4, v255, 29
	s_add_u32 s2, s2, s4
	s_addc_u32 s3, s3, s49
	v_mov_b64_e32 v[2:3], 0x300
	v_cmp_lt_i64_e64 s[6:7], s[2:3], v[2:3]
	v_mov_b64_e32 v[2:3], 0x2ff
	v_cmp_gt_i64_e32 vcc, s[2:3], v[2:3]
	s_nop 3
	s_mov_b32 s101, s6
	s_cbranch_vccnz .LBB0_2153
	s_ashr_i32 s3, s2, 31
	s_lshr_b32 s3, s3, 29
	s_add_i32 s3, s2, s3
	s_ashr_i32 s4, s3, 3
	s_and_b32 s3, s3, -8
	s_sub_i32 s2, s2, s3
	s_cmp_lt_i32 s2, 0
	s_movk_i32 s3, 0x61
	s_cselect_b32 s3, s3, 0x60
	s_mul_i32 s2, s2, s3
	s_add_i32 s2, s2, s4
	s_ashr_i32 s3, s2, 31
	s_lshr_b32 s3, s3, 26
	s_add_i32 s3, s2, s3
	s_ashr_i32 s4, s3, 6
	s_lshl_b32 s4, s4, 3
	s_sub_i32 s5, 0x60, s4
	s_min_i32 s5, s5, 8
	s_andn2_b32 s3, s3, 63
	s_sub_i32 s2, s2, s3
	s_ashr_i32 s56, s2, 3
	s_and_b32 s2, s2, 7
	s_add_i32 s57, s4, s2
